# XCC-local barriers: per-workgroup slot stores + one wave-wide poll load (no returning atomic), replaces the counter-poll variant
# baseline (speedup 1.0000x reference)
_Z14fwd_megakernel4Args:
	s_mov_b32 s100, 0
	s_load_dword s94, s[0:1], 0xc8
	s_mov_b32 s95, s2
	s_add_u32 s2, s0, 0xc8
	s_addc_u32 s3, s1, 0
	v_readfirstlane_b32 s8, v0
	v_writelane_b32 v252, s2, 0
	s_nop 1
	v_writelane_b32 v252, s3, 1
	s_waitcnt lgkmcnt(0)
	s_and_b32 s2, s94, 7
	s_cmp_lg_u32 s2, 0
	s_mov_b32 s2, s95
	s_cbranch_scc1 .LBB0_2
	s_ashr_i32 s3, s95, 31
	s_lshr_b32 s3, s3, 29
	s_add_i32 s3, s95, s3
	s_ashr_i32 s4, s3, 3
	s_and_b32 s3, s3, -8
	s_ashr_i32 s2, s94, 3
	s_sub_i32 s3, s95, s3
	s_mul_i32 s2, s2, s3
	s_add_i32 s2, s2, s4

.LBB0_347:
	s_and_b64 vcc, exec, s[0:1]
	s_cbranch_vccz .LBB0_367
	s_waitcnt vmcnt(0)
	s_waitcnt vmcnt(0)
	s_barrier
	s_mov_b64 s[0:1], exec
	v_readlane_b32 s2, v252, 8
	v_readlane_b32 s3, v252, 9
	s_and_b64 s[2:3], s[0:1], s[2:3]
	s_mov_b64 exec, s[2:3]
	s_cbranch_execz .LBB0_366
	s_add_i32 s100, s100, 1
	v_mov_b32_e32 v1, 0x20000
	s_waitcnt vmcnt(0) expcnt(0) lgkmcnt(0)
	ds_read2_b32 v[2:3], v1 offset1:3
	v_readlane_b32 s2, v252, 7
	s_lshl_b32 s2, s2, 8
	v_readlane_b32 s6, v252, 5
	v_readlane_b32 s7, v252, 6
	s_add_u32 s2, s6, s2
	s_addc_u32 s3, s7, 0
	v_mov_b32_e32 v4, s100
	s_waitcnt lgkmcnt(0)
	v_readfirstlane_b32 s4, v2
	v_lshlrev_b32_e32 v3, 2, v3
	v_add_u32_e32 v3, 0x3000, v3
	global_store_dword v3, v4, s[2:3] offset:1536
	s_bfm_b64 exec, s4, 0
	v_mbcnt_lo_u32_b32 v5, -1, 0
	v_mbcnt_hi_u32_b32 v5, -1, v5
	v_lshlrev_b32_e32 v5, 2, v5
	v_add_u32_e32 v5, 0x3000, v5
	s_mov_b32 s101, 0
my_lb_poll_5:
	global_load_dword v6, v5, s[2:3] offset:1536 sc1
	s_add_i32 s101, s101, 1
	s_waitcnt vmcnt(0)
	v_cmp_gt_u32_e32 vcc, s100, v6
	s_cmp_eq_u64 vcc, 0
	s_cbranch_scc1 my_lb_done_5
	s_cmp_lt_u32 s101, 0x8000
	s_cbranch_scc0 my_lb_done_5
	s_sleep 1
	s_branch my_lb_poll_5
my_lb_done_5:
	buffer_inv sc1
	s_waitcnt vmcnt(0)

my_lb_poll_4:
	global_load_dword v6, v5, s[2:3] offset:1536 sc1
	s_add_i32 s101, s101, 1
	s_waitcnt vmcnt(0)
	v_cmp_gt_u32_e32 vcc, s100, v6
	s_cmp_eq_u64 vcc, 0
	s_cbranch_scc1 my_lb_done_4
	s_cmp_lt_u32 s101, 0x8000
	s_cbranch_scc0 my_lb_done_4
	s_sleep 1
	s_branch my_lb_poll_4
my_lb_done_4:
	buffer_inv sc1
	s_waitcnt vmcnt(0)

my_lb_poll_3:
	global_load_dword v6, v5, s[2:3] offset:1536 sc1
	s_add_i32 s101, s101, 1
	s_waitcnt vmcnt(0)
	v_cmp_gt_u32_e32 vcc, s100, v6
	s_cmp_eq_u64 vcc, 0
	s_cbranch_scc1 my_lb_done_3
	s_cmp_lt_u32 s101, 0x8000
	s_cbranch_scc0 my_lb_done_3
	s_sleep 1
	s_branch my_lb_poll_3
my_lb_done_3:
	buffer_inv sc1
	s_waitcnt vmcnt(0)

my_lb_poll_2:
	global_load_dword v6, v5, s[2:3] offset:1536 sc1
	s_add_i32 s101, s101, 1
	s_waitcnt vmcnt(0)
	v_cmp_gt_u32_e32 vcc, s100, v6
	s_cmp_eq_u64 vcc, 0
	s_cbranch_scc1 my_lb_done_2
	s_cmp_lt_u32 s101, 0x8000
	s_cbranch_scc0 my_lb_done_2
	s_sleep 1
	s_branch my_lb_poll_2
my_lb_done_2:
	buffer_inv sc1
	s_waitcnt vmcnt(0)

my_lb_poll_1:
	global_load_dword v6, v5, s[2:3] offset:1536 sc1
	s_add_i32 s101, s101, 1
	s_waitcnt vmcnt(0)
	v_cmp_gt_u32_e32 vcc, s100, v6
	s_cmp_eq_u64 vcc, 0
	s_cbranch_scc1 my_lb_done_1
	s_cmp_lt_u32 s101, 0x8000
	s_cbranch_scc0 my_lb_done_1
	s_sleep 1
	s_branch my_lb_poll_1
my_lb_done_1:
	buffer_inv sc1
	s_waitcnt vmcnt(0)

.LBB0_1345:
	s_and_b64 vcc, exec, s[0:1]
	s_cbranch_vccz .LBB0_1365
	s_waitcnt vmcnt(0)
	s_waitcnt vmcnt(0) lgkmcnt(0)
	s_barrier
	s_mov_b64 s[0:1], exec
	v_readlane_b32 s2, v252, 8
	v_readlane_b32 s3, v252, 9
	s_and_b64 s[2:3], s[0:1], s[2:3]
	s_mov_b64 exec, s[2:3]
	s_cbranch_execz .LBB0_1364
	s_add_i32 s100, s100, 1
	v_mov_b32_e32 v1, 0x20000
	s_waitcnt vmcnt(0) expcnt(0) lgkmcnt(0)
	ds_read2_b32 v[2:3], v1 offset1:3
	v_readlane_b32 s2, v252, 7
	s_lshl_b32 s2, s2, 8
	v_readlane_b32 s6, v252, 5
	v_readlane_b32 s7, v252, 6
	s_add_u32 s2, s6, s2
	s_addc_u32 s3, s7, 0
	v_mov_b32_e32 v4, s100
	s_waitcnt lgkmcnt(0)
	v_readfirstlane_b32 s4, v2
	v_lshlrev_b32_e32 v3, 2, v3
	v_add_u32_e32 v3, 0x3000, v3
	global_store_dword v3, v4, s[2:3] offset:1536
	s_bfm_b64 exec, s4, 0
	v_mbcnt_lo_u32_b32 v5, -1, 0
	v_mbcnt_hi_u32_b32 v5, -1, v5
	v_lshlrev_b32_e32 v5, 2, v5
	v_add_u32_e32 v5, 0x3000, v5
	s_mov_b32 s101, 0
my_lb_poll_0:
	global_load_dword v6, v5, s[2:3] offset:1536 sc1
	s_add_i32 s101, s101, 1
	s_waitcnt vmcnt(0)
	v_cmp_gt_u32_e32 vcc, s100, v6
	s_cmp_eq_u64 vcc, 0
	s_cbranch_scc1 my_lb_done_0
	s_cmp_lt_u32 s101, 0x8000
	s_cbranch_scc0 my_lb_done_0
	s_sleep 1
	s_branch my_lb_poll_0
my_lb_done_0:
	buffer_inv sc1
	s_waitcnt vmcnt(0)
